# NSA selected branch: fast paths for unmasked both-block and single-block chunks
# speedup vs baseline: 1.0119x; 1.0004x over previous
.LBB0_352:
	v_cmp_le_i32_e32 vcc, s68, v123
	s_and_saveexec_b64 s[40:41], vcc
	s_cbranch_execz .LBB0_370
	s_lshr_b32 s2, s68, 6
	s_cmpk_lt_u32 s68, 0x1000
	s_cselect_b64 vcc, -1, 0
	s_sub_i32 s3, s2, 64
	s_and_b64 s[0:1], vcc, exec
	s_cselect_b32 s0, 1, 0xffffffc1
	v_cndmask_b32_e32 v35, v117, v119, vcc
	v_cndmask_b32_e32 v34, v128, v130, vcc
	s_cselect_b32 s1, s2, s3
	s_add_i32 s0, s0, s2
	v_lshrrev_b64 v[36:37], s1, v[34:35]
	v_lshrrev_b64 v[34:35], s0, v[34:35]
	v_and_b32_e32 v1, 1, v36
	v_and_b32_e32 v34, 1, v34
	s_add_i32 s2, s68, 61
	v_cmp_eq_u32_e32 vcc, 1, v1
	v_cmp_eq_u32_e64 s[50:51], 1, v34
	v_cmp_ne_u32_e64 s[0:1], 0, v1
	v_cmp_le_i32_e64 s[2:3], s2, v176
	s_mov_b64 s[4:5], 0
	s_and_saveexec_b64 s[6:7], s[2:3]
	v_cndmask_b32_e64 v1, 0, 1, s[50:51]
	v_cmp_ne_u32_e64 s[2:3], 0, v1
	s_cmp_lg_u64 s[2:3], 0
	s_cselect_b64 s[2:3], -1, 0
	s_and_b64 s[4:5], s[2:3], exec
	s_or_b64 exec, exec, s[6:7]
	s_cmp_lg_u64 s[0:1], 0
	s_cselect_b64 s[0:1], -1, 0
	s_bitcmp1_b32 s8, 0
	s_cselect_b32 s2, 0x9000, 0
	s_add_i32 s90, s2, 0
	s_and_b64 s[2:3], s[0:1], s[4:5]
	s_xor_b64 s[2:3], s[2:3], -1
	s_and_saveexec_b64 s[6:7], s[2:3]
	s_xor_b64 s[62:63], exec, s[6:7]
	s_cbranch_execz .LBB0_363
	s_or_b64 s[2:3], s[0:1], s[4:5]
	s_and_saveexec_b64 s[64:65], s[2:3]
	s_cbranch_execz .LBB0_362
	s_and_b64 s[2:3], s[0:1], exec
	s_cselect_b32 s2, 0, 64
	v_cndmask_b32_e64 v1, 0, 1, vcc
	v_cndmask_b32_e64 v34, 0, 1, s[50:51]
	v_cndmask_b32_e64 v1, v34, v1, s[0:1]
	s_mul_i32 s3, s2, 0x90
	v_and_b32_e32 v1, 1, v1
	s_add_i32 s70, s90, s3
	v_cmp_eq_u32_e64 s[0:1], 1, v1
	v_readfirstlane_b32 s4, v176
	s_add_i32 s3, s2, s68
	s_add_i32 s3, s3, 63
	s_cmp_le_i32 s3, s4
	s_cbranch_scc0 .Lnsa_single_slow
	v_add3_u32 v1, s70, v151, v152
	v_add3_u32 v179, s70, v154, v155
	ds_read_b128 v[180:183], v1
	ds_read_b128 v[184:187], v1 offset:4608
	ds_read_b128 v[188:191], v1 offset:32
	ds_read_b128 v[192:195], v1 offset:4640
	ds_read_b128 v[196:199], v1 offset:64
	ds_read_b128 v[200:203], v1 offset:4672
	ds_read_b128 v[204:207], v1 offset:96
	ds_read_b128 v[208:211], v1 offset:4704
	v_mov_b32_e32 v220, s87
	v_cndmask_b32_e64 v142, v234, -v220, s[0:1]
	v_mov_b32_e32 v168, 0x3e38aa3b
	s_waitcnt lgkmcnt(6)
	v_mfma_f32_32x32x16_bf16 v[34:49], v[180:183], v[98:101], 0
	v_mfma_f32_32x32x16_bf16 v[50:65], v[184:187], v[98:101], 0
	s_waitcnt lgkmcnt(4)
	v_mfma_f32_32x32x16_bf16 v[34:49], v[188:191], v[102:105], v[34:49]
	v_mfma_f32_32x32x16_bf16 v[50:65], v[192:195], v[102:105], v[50:65]
	s_waitcnt lgkmcnt(2)
	v_mfma_f32_32x32x16_bf16 v[34:49], v[196:199], v[106:109], v[34:49]
	v_mfma_f32_32x32x16_bf16 v[50:65], v[200:203], v[106:109], v[50:65]
	s_waitcnt lgkmcnt(0)
	v_mfma_f32_32x32x16_bf16 v[34:49], v[204:207], v[110:113], v[34:49]
	v_mfma_f32_32x32x16_bf16 v[50:65], v[208:211], v[110:113], v[50:65]
	ds_read_b64_tr_b16 v[212:213], v179 offset:18432
	ds_read_b64_tr_b16 v[214:215], v179 offset:19584
	ds_read_b64_tr_b16 v[216:217], v179 offset:18496
	ds_read_b64_tr_b16 v[218:219], v179 offset:19648
	ds_read_b64_tr_b16 v[236:237], v179 offset:20736
	ds_read_b64_tr_b16 v[238:239], v179 offset:21888
	ds_read_b64_tr_b16 v[240:241], v179 offset:20800
	ds_read_b64_tr_b16 v[242:243], v179 offset:21952
	ds_read_b64_tr_b16 v[244:245], v179 offset:23040
	ds_read_b64_tr_b16 v[246:247], v179 offset:24192
	v_mov_b64_e32 v[220:221], 0
	s_nop 7
	v_pk_fma_f32 v[34:35], v[34:35], v[168:169], v[142:143] op_sel_hi:[1,0,0]
	v_pk_fma_f32 v[36:37], v[36:37], v[168:169], v[142:143] op_sel_hi:[1,0,0]
	v_pk_fma_f32 v[38:39], v[38:39], v[168:169], v[142:143] op_sel_hi:[1,0,0]
	v_pk_fma_f32 v[40:41], v[40:41], v[168:169], v[142:143] op_sel_hi:[1,0,0]
	v_pk_fma_f32 v[42:43], v[42:43], v[168:169], v[142:143] op_sel_hi:[1,0,0]
	v_pk_fma_f32 v[44:45], v[44:45], v[168:169], v[142:143] op_sel_hi:[1,0,0]
	v_pk_fma_f32 v[46:47], v[46:47], v[168:169], v[142:143] op_sel_hi:[1,0,0]
	v_pk_fma_f32 v[48:49], v[48:49], v[168:169], v[142:143] op_sel_hi:[1,0,0]
	v_exp_f32_e32 v34, v34
	v_exp_f32_e32 v35, v35
	v_exp_f32_e32 v36, v36
	v_exp_f32_e32 v37, v37
	v_exp_f32_e32 v38, v38
	v_exp_f32_e32 v39, v39
	v_exp_f32_e32 v40, v40
	v_exp_f32_e32 v41, v41
	v_exp_f32_e32 v42, v42
	v_exp_f32_e32 v43, v43
	v_exp_f32_e32 v44, v44
	v_exp_f32_e32 v45, v45
	v_exp_f32_e32 v46, v46
	v_exp_f32_e32 v47, v47
	v_exp_f32_e32 v48, v48
	v_exp_f32_e32 v49, v49
	v_pk_fma_f32 v[50:51], v[50:51], v[168:169], v[142:143] op_sel_hi:[1,0,0]
	v_pk_fma_f32 v[52:53], v[52:53], v[168:169], v[142:143] op_sel_hi:[1,0,0]
	v_pk_fma_f32 v[54:55], v[54:55], v[168:169], v[142:143] op_sel_hi:[1,0,0]
	v_pk_fma_f32 v[56:57], v[56:57], v[168:169], v[142:143] op_sel_hi:[1,0,0]
	v_pk_fma_f32 v[58:59], v[58:59], v[168:169], v[142:143] op_sel_hi:[1,0,0]
	v_pk_fma_f32 v[60:61], v[60:61], v[168:169], v[142:143] op_sel_hi:[1,0,0]
	v_pk_fma_f32 v[62:63], v[62:63], v[168:169], v[142:143] op_sel_hi:[1,0,0]
	v_pk_fma_f32 v[64:65], v[64:65], v[168:169], v[142:143] op_sel_hi:[1,0,0]
	v_exp_f32_e32 v50, v50
	v_exp_f32_e32 v51, v51
	v_exp_f32_e32 v52, v52
	v_exp_f32_e32 v53, v53
	v_exp_f32_e32 v54, v54
	v_exp_f32_e32 v55, v55
	v_exp_f32_e32 v56, v56
	v_exp_f32_e32 v57, v57
	v_exp_f32_e32 v58, v58
	v_exp_f32_e32 v59, v59
	v_exp_f32_e32 v60, v60
	v_exp_f32_e32 v61, v61
	v_exp_f32_e32 v62, v62
	v_exp_f32_e32 v63, v63
	v_exp_f32_e32 v64, v64
	v_exp_f32_e32 v65, v65
	v_pk_add_f32 v[220:221], v[34:35], v[220:221]
	v_pk_add_f32 v[220:221], v[36:37], v[220:221]
	v_pk_add_f32 v[220:221], v[38:39], v[220:221]
	v_pk_add_f32 v[220:221], v[40:41], v[220:221]
	v_pk_add_f32 v[220:221], v[42:43], v[220:221]
	v_pk_add_f32 v[220:221], v[44:45], v[220:221]
	v_pk_add_f32 v[220:221], v[46:47], v[220:221]
	v_pk_add_f32 v[220:221], v[48:49], v[220:221]
	v_cvt_pk_bf16_f32 v34, v34, v35
	v_cvt_pk_bf16_f32 v35, v36, v37
	v_cvt_pk_bf16_f32 v36, v38, v39
	v_cvt_pk_bf16_f32 v37, v40, v41
	v_cvt_pk_bf16_f32 v42, v42, v43
	v_cvt_pk_bf16_f32 v43, v44, v45
	v_cvt_pk_bf16_f32 v44, v46, v47
	v_cvt_pk_bf16_f32 v45, v48, v49
	v_pk_add_f32 v[220:221], v[50:51], v[220:221]
	v_pk_add_f32 v[220:221], v[52:53], v[220:221]
	v_pk_add_f32 v[220:221], v[54:55], v[220:221]
	v_pk_add_f32 v[220:221], v[56:57], v[220:221]
	v_pk_add_f32 v[220:221], v[58:59], v[220:221]
	v_pk_add_f32 v[220:221], v[60:61], v[220:221]
	v_pk_add_f32 v[220:221], v[62:63], v[220:221]
	v_pk_add_f32 v[220:221], v[64:65], v[220:221]
	v_cvt_pk_bf16_f32 v50, v50, v51
	v_cvt_pk_bf16_f32 v51, v52, v53
	v_cvt_pk_bf16_f32 v52, v54, v55
	v_cvt_pk_bf16_f32 v53, v56, v57
	v_cvt_pk_bf16_f32 v58, v58, v59
	v_cvt_pk_bf16_f32 v59, v60, v61
	v_cvt_pk_bf16_f32 v60, v62, v63
	v_cvt_pk_bf16_f32 v61, v64, v65
	v_add_f32_e32 v143, v143, v220
	v_add_f32_e32 v143, v143, v221
	s_waitcnt lgkmcnt(8)
	v_mfma_f32_32x32x16_bf16 v[18:33], v[212:215], v[34:37], v[18:33]
	ds_read_b64_tr_b16 v[248:249], v179 offset:23104
	ds_read_b64_tr_b16 v[250:251], v179 offset:24256
	s_waitcnt lgkmcnt(8)
	v_mfma_f32_32x32x16_bf16 v[2:17], v[216:219], v[34:37], v[2:17]
	ds_read_b64_tr_b16 v[212:213], v179 offset:25344
	ds_read_b64_tr_b16 v[214:215], v179 offset:26496
	s_waitcnt lgkmcnt(8)
	v_mfma_f32_32x32x16_bf16 v[18:33], v[236:239], v[42:45], v[18:33]
	ds_read_b64_tr_b16 v[216:217], v179 offset:25408
	ds_read_b64_tr_b16 v[218:219], v179 offset:26560
	s_waitcnt lgkmcnt(8)
	v_mfma_f32_32x32x16_bf16 v[2:17], v[240:243], v[42:45], v[2:17]
	s_waitcnt lgkmcnt(6)
	v_mfma_f32_32x32x16_bf16 v[18:33], v[244:247], v[50:53], v[18:33]
	s_waitcnt lgkmcnt(4)
	v_mfma_f32_32x32x16_bf16 v[2:17], v[248:251], v[50:53], v[2:17]
	s_waitcnt lgkmcnt(2)
	v_mfma_f32_32x32x16_bf16 v[18:33], v[212:215], v[58:61], v[18:33]
	s_waitcnt lgkmcnt(0)
	v_mfma_f32_32x32x16_bf16 v[2:17], v[216:219], v[58:61], v[2:17]
	s_branch .LBB0_362
.Lnsa_single_slow:
	v_add3_u32 v1, s70, v151, v152
	ds_read_b128 v[34:37], v1 offset:4608
	ds_read_b128 v[38:41], v1
	ds_read_b128 v[66:69], v1 offset:32
	ds_read_b128 v[70:73], v1 offset:4640
	s_waitcnt lgkmcnt(0)
	v_mfma_f32_32x32x16_bf16 v[50:65], v[38:41], v[98:101], 0
	s_add_i32 s2, s2, s68
	v_mfma_f32_32x32x16_bf16 v[34:49], v[34:37], v[98:101], 0
	v_mfma_f32_32x32x16_bf16 v[50:65], v[66:69], v[102:105], v[50:65]
	v_mfma_f32_32x32x16_bf16 v[34:49], v[70:73], v[102:105], v[34:49]
	ds_read_b128 v[66:69], v1 offset:64
	ds_read_b128 v[70:73], v1 offset:4672
	s_waitcnt lgkmcnt(0)
	v_mfma_f32_32x32x16_bf16 v[50:65], v[66:69], v[106:109], v[50:65]
	v_mfma_f32_32x32x16_bf16 v[34:49], v[70:73], v[106:109], v[34:49]
	ds_read_b128 v[66:69], v1 offset:96
	ds_read_b128 v[70:73], v1 offset:4704
	v_mov_b32_e32 v1, s87
	s_waitcnt lgkmcnt(0)
	v_mfma_f32_32x32x16_bf16 v[50:65], v[66:69], v[110:113], v[50:65]
	v_cndmask_b32_e64 v68, v234, -v1, s[0:1]
	s_add_i32 s0, s2, 63
	v_cmp_le_i32_e64 s[0:1], s0, v176
	v_mfma_f32_32x32x16_bf16 v[34:49], v[70:73], v[110:113], v[34:49]
	s_nop 7
	v_fmamk_f32 v1, v50, 0x3e38aa3b, v68
	v_fmamk_f32 v142, v51, 0x3e38aa3b, v68
	v_fmamk_f32 v97, v52, 0x3e38aa3b, v68
	v_fmamk_f32 v96, v53, 0x3e38aa3b, v68
	v_fmamk_f32 v95, v54, 0x3e38aa3b, v68
	v_fmamk_f32 v94, v55, 0x3e38aa3b, v68
	v_fmamk_f32 v93, v56, 0x3e38aa3b, v68
	v_fmamk_f32 v92, v57, 0x3e38aa3b, v68
	v_fmamk_f32 v90, v58, 0x3e38aa3b, v68
	v_fmamk_f32 v91, v59, 0x3e38aa3b, v68
	v_fmamk_f32 v89, v60, 0x3e38aa3b, v68
	v_fmamk_f32 v88, v61, 0x3e38aa3b, v68
	v_fmamk_f32 v87, v62, 0x3e38aa3b, v68
	v_fmamk_f32 v86, v63, 0x3e38aa3b, v68
	v_fmamk_f32 v85, v64, 0x3e38aa3b, v68
	v_fmamk_f32 v84, v65, 0x3e38aa3b, v68
	v_fmamk_f32 v83, v34, 0x3e38aa3b, v68
	v_fmamk_f32 v82, v35, 0x3e38aa3b, v68
	v_fmamk_f32 v81, v36, 0x3e38aa3b, v68
	v_fmamk_f32 v80, v37, 0x3e38aa3b, v68
	v_fmamk_f32 v79, v38, 0x3e38aa3b, v68
	v_fmamk_f32 v78, v39, 0x3e38aa3b, v68
	v_fmamk_f32 v77, v40, 0x3e38aa3b, v68
	v_fmamk_f32 v76, v41, 0x3e38aa3b, v68
	v_fmamk_f32 v75, v42, 0x3e38aa3b, v68
	v_fmamk_f32 v74, v43, 0x3e38aa3b, v68
	v_fmamk_f32 v73, v44, 0x3e38aa3b, v68
	v_fmamk_f32 v72, v45, 0x3e38aa3b, v68
	v_fmamk_f32 v71, v46, 0x3e38aa3b, v68
	v_fmamk_f32 v70, v47, 0x3e38aa3b, v68
	v_fmamk_f32 v69, v48, 0x3e38aa3b, v68
	v_fmac_f32_e32 v68, 0x3e38aa3b, v49
	s_and_saveexec_b64 s[4:5], s[0:1]
	s_xor_b64 s[0:1], exec, s[4:5]
	s_cbranch_execz .LBB0_359
	v_exp_f32_e32 v38, v1
	v_exp_f32_e32 v39, v142
	v_exp_f32_e32 v34, v83
	v_exp_f32_e32 v52, v97
	v_exp_f32_e32 v35, v82
	v_exp_f32_e32 v53, v96
	v_exp_f32_e32 v36, v81
	v_exp_f32_e32 v58, v95
	v_exp_f32_e32 v37, v80
	v_add_f32_e32 v1, 0, v38
	v_exp_f32_e32 v59, v94
	v_mov_b32_e32 v44, v34
	v_mov_b32_e32 v45, v39
	v_exp_f32_e32 v40, v79
	v_pk_add_f32 v[44:45], v[44:45], v[0:1]
	v_mov_b32_e32 v48, v35
	v_mov_b32_e32 v49, v52
	v_pk_add_f32 v[44:45], v[48:49], v[44:45]
	v_mov_b32_e32 v48, v36
	v_mov_b32_e32 v49, v53
	v_pk_add_f32 v[44:45], v[48:49], v[44:45]
	v_mov_b32_e32 v48, v37
	v_mov_b32_e32 v49, v58
	v_pk_add_f32 v[44:45], v[48:49], v[44:45]
	v_mov_b32_e32 v41, v59
	v_exp_f32_e32 v62, v93
	v_pk_add_f32 v[64:65], v[40:41], v[44:45]
	v_exp_f32_e32 v41, v78
	v_exp_f32_e32 v63, v92
	v_exp_f32_e32 v60, v77
	v_exp_f32_e32 v42, v90
	v_exp_f32_e32 v61, v76
	v_exp_f32_e32 v43, v91
	v_exp_f32_e32 v44, v75
	v_exp_f32_e32 v46, v89
	v_exp_f32_e32 v45, v74
	v_mov_b32_e32 v66, v41
	v_mov_b32_e32 v67, v62
	v_exp_f32_e32 v47, v88
	v_exp_f32_e32 v48, v73
	v_pk_add_f32 v[64:65], v[66:67], v[64:65]
	v_mov_b32_e32 v66, v60
	v_mov_b32_e32 v67, v63
	v_exp_f32_e32 v50, v87
	v_exp_f32_e32 v49, v72
	v_pk_add_f32 v[64:65], v[66:67], v[64:65]
	v_mov_b32_e32 v66, v61
	v_mov_b32_e32 v67, v42
	v_exp_f32_e32 v51, v86
	v_exp_f32_e32 v54, v71
	v_pk_add_f32 v[64:65], v[66:67], v[64:65]
	v_mov_b32_e32 v66, v44
	v_mov_b32_e32 v67, v43
	v_exp_f32_e32 v56, v85
	v_exp_f32_e32 v55, v70
	v_pk_add_f32 v[64:65], v[66:67], v[64:65]
	v_mov_b32_e32 v66, v45
	v_mov_b32_e32 v67, v46
	v_pk_add_f32 v[64:65], v[66:67], v[64:65]
	v_mov_b32_e32 v66, v48
	v_mov_b32_e32 v67, v47
	v_pk_add_f32 v[64:65], v[66:67], v[64:65]
	v_mov_b32_e32 v66, v49
	v_mov_b32_e32 v67, v50
	v_pk_add_f32 v[64:65], v[66:67], v[64:65]
	v_mov_b32_e32 v66, v54
	v_mov_b32_e32 v67, v51
	v_exp_f32_e32 v57, v84
	v_pk_add_f32 v[64:65], v[66:67], v[64:65]
	v_mov_b32_e32 v66, v55
	v_mov_b32_e32 v67, v56
	v_pk_add_f32 v[66:67], v[66:67], v[64:65]
	v_exp_f32_e32 v64, v69
	v_mov_b32_e32 v65, v57
	v_pk_add_f32 v[66:67], v[64:65], v[66:67]
